# P5/P7 residual (read-once) loads marked nt so they do not displace a5/h3 in L2/MALL
# speedup vs baseline: 1.0052x; 1.0052x over previous
; __device__ __forceinline__ unsigned cvt_pk_bf16(float lo, float hi) { unsigned r; asm volatile("v_cvt_pk_bf16_f32 %0, %1, %2" : "=v"(r) : "v"(lo), "v"(hi)); return r; }
;     __device__ __forceinline__ void operator()(const f32x4 (&acc)[2][2][4][2], const Unit& u, int wr, int wc, int fr, int fq) const {
;         const int row0 = u.pm * BM + wr * 64 + fr, col0 = u.pn * BM + wc * 32 + 4 * fq;
; #pragma unroll
;         for (int ai = 0; ai < 2; ++ai)
; #pragma unroll
;             for (int m = 0; m < 4; ++m) { const int row = row0 + ai * HALF + m * 16; const size_t ro = (size_t)row * 2048 + col0; float ss = 0.f;
; #pragma unroll
;                 for (int bj = 0; bj < 2; ++bj)
; #pragma unroll
;                     for (int n = 0; n < 2; ++n) { const size_t off = ro + bj * HALF + n * 16; const f32x4 hv = *(const f32x4*)(R + off) + acc[ai][bj][m][n];
;                         *(f32x4*)(H + off) = hv; ss += (hv[0] * hv[0] + hv[1] * hv[1]) + (hv[2] * hv[2] + hv[3] * hv[3]);
;                         if (WITH_A5) { const f32x4 gv = *(const f32x4*)(gm + col0 + bj * HALF + n * 16); u32x2 w; w.x = cvt_pk_bf16(hv[0] * gv[0], hv[1] * gv[1]); w.y = cvt_pk_bf16(hv[2] * gv[2], hv[3] * gv[3]); *(u32x2*)(a5 + off) = w; } }
.LBB0_736:
	v_lshlrev_b32_e32 v222, 13, v146
	v_lshl_add_u32 v222, v148, 2, v222
	v_lshlrev_b32_e32 v153, 2, v146
	v_lshrrev_b32_e32 v223, 1, v222
	v_lshlrev_b32_e32 v154, 2, v148
	v_xor_b32_e32 v144, 16, v152
	v_xor_b32_e32 v145, 32, v152
	v_lshlrev_b32_e32 v144, 2, v144
	v_lshlrev_b32_e32 v145, 2, v145
	v_readlane_b32 s52, v234, 5
	v_readlane_b32 s53, v234, 6
	v_readlane_b32 s60, v234, 31
	v_readlane_b32 s61, v234, 32
	s_lshl_b32 s62, s2, 21
	s_lshl_b32 s63, s26, 10
	s_add_u32 s62, s62, s63
	s_nop 1
	s_add_u32 s52, s52, s62
	s_addc_u32 s53, s53, 0
	s_add_u32 s54, s86, s62
	s_addc_u32 s55, s87, 0
	s_add_u32 s60, s60, s63
	s_addc_u32 s61, s61, 0
	s_lshr_b32 s63, s62, 1
	s_add_u32 s56, s10, s63
	s_addc_u32 s57, s11, 0
	s_lshl_b32 s63, s2, 10
	s_add_u32 s58, s12, s63
	s_addc_u32 s59, s13, 0
	global_load_dwordx4 v[158:161], v154, s[60:61]
	global_load_dwordx4 v[162:165], v154, s[60:61] offset:64
	global_load_dwordx4 v[166:169], v154, s[60:61] offset:512
	global_load_dwordx4 v[170:173], v154, s[60:61] offset:576
	global_load_dwordx4 v[174:177], v222, s[52:53] nt
	global_load_dwordx4 v[178:181], v222, s[52:53] offset:64 nt
	global_load_dwordx4 v[182:185], v222, s[52:53] offset:512 nt
	global_load_dwordx4 v[186:189], v222, s[52:53] offset:576 nt
	s_add_u32 s52, s52, 0x20000
	s_addc_u32 s53, s53, 0
	global_load_dwordx4 v[190:193], v222, s[52:53] nt
	global_load_dwordx4 v[194:197], v222, s[52:53] offset:64 nt
	global_load_dwordx4 v[198:201], v222, s[52:53] offset:512 nt
	global_load_dwordx4 v[202:205], v222, s[52:53] offset:576 nt
	s_add_u32 s52, s52, 0x20000
	s_addc_u32 s53, s53, 0
	global_load_dwordx4 v[206:209], v222, s[52:53] nt
	global_load_dwordx4 v[210:213], v222, s[52:53] offset:64 nt
	global_load_dwordx4 v[214:217], v222, s[52:53] offset:512 nt
	global_load_dwordx4 v[218:221], v222, s[52:53] offset:576 nt
	s_add_u32 s52, s52, 0x20000
	s_addc_u32 s53, s53, 0
	s_waitcnt vmcnt(8)
	v_pk_add_f32 v[124:125], v[124:125], v[174:175]
	v_pk_add_f32 v[126:127], v[126:127], v[176:177]
	v_pk_add_f32 v[120:121], v[120:121], v[178:179]
	v_pk_add_f32 v[122:123], v[122:123], v[180:181]
	v_pk_add_f32 v[116:117], v[116:117], v[182:183]
	v_pk_add_f32 v[118:119], v[118:119], v[184:185]
	v_pk_add_f32 v[112:113], v[112:113], v[186:187]
	v_pk_add_f32 v[114:115], v[114:115], v[188:189]
	global_load_dwordx4 v[174:177], v222, s[52:53] nt
	global_load_dwordx4 v[178:181], v222, s[52:53] offset:64 nt
	global_load_dwordx4 v[182:185], v222, s[52:53] offset:512 nt
	global_load_dwordx4 v[186:189], v222, s[52:53] offset:576 nt
	s_add_u32 s52, s52, 0xa0000
	s_addc_u32 s53, s53, 0
	global_store_dwordx4 v222, v[124:127], s[54:55]
	global_store_dwordx4 v222, v[120:123], s[54:55] offset:64
	global_store_dwordx4 v222, v[116:119], s[54:55] offset:512
	global_store_dwordx4 v222, v[112:115], s[54:55] offset:576
	s_add_u32 s54, s54, 0x20000
	s_addc_u32 s55, s55, 0
	v_mul_f32_e32 v140, v124, v158
	v_mul_f32_e32 v141, v125, v159
	v_mul_f32_e32 v142, v126, v160
	v_mul_f32_e32 v143, v127, v161
	v_cvt_pk_bf16_f32 v224, v140, v141
	v_cvt_pk_bf16_f32 v225, v142, v143
	global_store_dwordx2 v223, v[224:225], s[56:57]
	v_mul_f32_e32 v140, v120, v162
	v_mul_f32_e32 v141, v121, v163
	v_mul_f32_e32 v142, v122, v164
	v_mul_f32_e32 v143, v123, v165
	v_cvt_pk_bf16_f32 v226, v140, v141
	v_cvt_pk_bf16_f32 v227, v142, v143
	global_store_dwordx2 v223, v[226:227], s[56:57] offset:32
	v_mul_f32_e32 v140, v116, v166
	v_mul_f32_e32 v141, v117, v167
	v_mul_f32_e32 v142, v118, v168
	v_mul_f32_e32 v143, v119, v169
	v_cvt_pk_bf16_f32 v228, v140, v141
	v_cvt_pk_bf16_f32 v229, v142, v143
	global_store_dwordx2 v223, v[228:229], s[56:57] offset:256
	v_mul_f32_e32 v140, v112, v170
	v_mul_f32_e32 v141, v113, v171
	v_mul_f32_e32 v142, v114, v172
	v_mul_f32_e32 v143, v115, v173
	v_cvt_pk_bf16_f32 v230, v140, v141
	v_cvt_pk_bf16_f32 v231, v142, v143
	global_store_dwordx2 v223, v[230:231], s[56:57] offset:288
	s_add_u32 s56, s56, 0x10000
	s_addc_u32 s57, s57, 0
	v_mul_f32_e32 v140, v125, v125
	v_mul_f32_e32 v141, v127, v127
	v_fmac_f32_e32 v140, v124, v124
	v_fmac_f32_e32 v141, v126, v126
	v_add_f32_e32 v142, v140, v141
	v_mul_f32_e32 v140, v121, v121
	v_mul_f32_e32 v141, v123, v123
	v_fmac_f32_e32 v140, v120, v120
	v_fmac_f32_e32 v141, v122, v122
	v_add_f32_e32 v140, v140, v141
	v_add_f32_e32 v142, v142, v140
	v_mul_f32_e32 v140, v117, v117
	v_mul_f32_e32 v141, v119, v119
	v_fmac_f32_e32 v140, v116, v116
	v_fmac_f32_e32 v141, v118, v118
	v_add_f32_e32 v140, v140, v141
	v_add_f32_e32 v142, v142, v140
	v_mul_f32_e32 v140, v113, v113
	v_mul_f32_e32 v141, v115, v115
	v_fmac_f32_e32 v140, v112, v112
	v_fmac_f32_e32 v141, v114, v114
	v_add_f32_e32 v140, v140, v141
	v_add_f32_e32 v142, v142, v140
	v_mov_b32_e32 v112, v142
	s_waitcnt vmcnt(16)
; __device__ __forceinline__ unsigned cvt_pk_bf16(float lo, float hi) { unsigned r; asm volatile("v_cvt_pk_bf16_f32 %0, %1, %2" : "=v"(r) : "v"(lo), "v"(hi)); return r; }
;     __device__ __forceinline__ void operator()(const f32x4 (&acc)[2][2][4][2], const Unit& u, int wr, int wc, int fr, int fq) const {
;     ...
;             for (int m = 0; m < 4; ++m) { const int row = row0 + ai * HALF + m * 16; const size_t ro = (size_t)row * 2048 + col0; float ss = 0.f;
; #pragma unroll
;                 for (int bj = 0; bj < 2; ++bj)
; #pragma unroll
;                     for (int n = 0; n < 2; ++n) { const size_t off = ro + bj * HALF + n * 16; const f32x4 hv = *(const f32x4*)(R + off) + acc[ai][bj][m][n];
;                         *(f32x4*)(H + off) = hv; ss += (hv[0] * hv[0] + hv[1] * hv[1]) + (hv[2] * hv[2] + hv[3] * hv[3]);
;                         if (WITH_A5) { const f32x4 gv = *(const f32x4*)(gm + col0 + bj * HALF + n * 16); u32x2 w; w.x = cvt_pk_bf16(hv[0] * gv[0], hv[1] * gv[1]); w.y = cvt_pk_bf16(hv[2] * gv[2], hv[3] * gv[3]); *(u32x2*)(a5 + off) = w; } }
	v_pk_add_f32 v[108:109], v[108:109], v[190:191]
	v_pk_add_f32 v[110:111], v[110:111], v[192:193]
	v_pk_add_f32 v[104:105], v[104:105], v[194:195]
	v_pk_add_f32 v[106:107], v[106:107], v[196:197]
	v_pk_add_f32 v[100:101], v[100:101], v[198:199]
	v_pk_add_f32 v[102:103], v[102:103], v[200:201]
	v_pk_add_f32 v[96:97], v[96:97], v[202:203]
	v_pk_add_f32 v[98:99], v[98:99], v[204:205]
	global_load_dwordx4 v[190:193], v222, s[52:53] nt
	global_load_dwordx4 v[194:197], v222, s[52:53] offset:64 nt
	global_load_dwordx4 v[198:201], v222, s[52:53] offset:512 nt
	global_load_dwordx4 v[202:205], v222, s[52:53] offset:576 nt
	s_add_u32 s52, s52, 0x20000
	s_addc_u32 s53, s53, 0
	global_store_dwordx4 v222, v[108:111], s[54:55]
	global_store_dwordx4 v222, v[104:107], s[54:55] offset:64
	global_store_dwordx4 v222, v[100:103], s[54:55] offset:512
	global_store_dwordx4 v222, v[96:99], s[54:55] offset:576
	s_add_u32 s54, s54, 0x20000
	s_addc_u32 s55, s55, 0
	v_mul_f32_e32 v140, v108, v158
	v_mul_f32_e32 v141, v109, v159
	v_mul_f32_e32 v142, v110, v160
	v_mul_f32_e32 v143, v111, v161
	v_cvt_pk_bf16_f32 v224, v140, v141
	v_cvt_pk_bf16_f32 v225, v142, v143
	global_store_dwordx2 v223, v[224:225], s[56:57]
	v_mul_f32_e32 v140, v104, v162
	v_mul_f32_e32 v141, v105, v163
	v_mul_f32_e32 v142, v106, v164
	v_mul_f32_e32 v143, v107, v165
	v_cvt_pk_bf16_f32 v226, v140, v141
	v_cvt_pk_bf16_f32 v227, v142, v143
	global_store_dwordx2 v223, v[226:227], s[56:57] offset:32
	v_mul_f32_e32 v140, v100, v166
	v_mul_f32_e32 v141, v101, v167
	v_mul_f32_e32 v142, v102, v168
	v_mul_f32_e32 v143, v103, v169
	v_cvt_pk_bf16_f32 v228, v140, v141
	v_cvt_pk_bf16_f32 v229, v142, v143
	global_store_dwordx2 v223, v[228:229], s[56:57] offset:256
	v_mul_f32_e32 v140, v96, v170
	v_mul_f32_e32 v141, v97, v171
	v_mul_f32_e32 v142, v98, v172
	v_mul_f32_e32 v143, v99, v173
	v_cvt_pk_bf16_f32 v230, v140, v141
	v_cvt_pk_bf16_f32 v231, v142, v143
	global_store_dwordx2 v223, v[230:231], s[56:57] offset:288
	s_add_u32 s56, s56, 0x10000
	s_addc_u32 s57, s57, 0
	v_mul_f32_e32 v140, v109, v109
	v_mul_f32_e32 v141, v111, v111
	v_fmac_f32_e32 v140, v108, v108
	v_fmac_f32_e32 v141, v110, v110
	v_add_f32_e32 v142, v140, v141
	v_mul_f32_e32 v140, v105, v105
	v_mul_f32_e32 v141, v107, v107
	v_fmac_f32_e32 v140, v104, v104
	v_fmac_f32_e32 v141, v106, v106
	v_add_f32_e32 v140, v140, v141
	v_add_f32_e32 v142, v142, v140
	v_mul_f32_e32 v140, v101, v101
	v_mul_f32_e32 v141, v103, v103
	v_fmac_f32_e32 v140, v100, v100
	v_fmac_f32_e32 v141, v102, v102
	v_add_f32_e32 v140, v140, v141
	v_add_f32_e32 v142, v142, v140
	v_mul_f32_e32 v140, v97, v97
	v_mul_f32_e32 v141, v99, v99
	v_fmac_f32_e32 v140, v96, v96
	v_fmac_f32_e32 v141, v98, v98
	v_add_f32_e32 v140, v140, v141
	v_add_f32_e32 v142, v142, v140
	v_mov_b32_e32 v96, v142
	s_waitcnt vmcnt(24)
	v_pk_add_f32 v[92:93], v[92:93], v[206:207]
	v_pk_add_f32 v[94:95], v[94:95], v[208:209]
	v_pk_add_f32 v[88:89], v[88:89], v[210:211]
	v_pk_add_f32 v[90:91], v[90:91], v[212:213]
	v_pk_add_f32 v[84:85], v[84:85], v[214:215]
	v_pk_add_f32 v[86:87], v[86:87], v[216:217]
	v_pk_add_f32 v[80:81], v[80:81], v[218:219]
	v_pk_add_f32 v[82:83], v[82:83], v[220:221]
	global_load_dwordx4 v[206:209], v222, s[52:53] nt
	global_load_dwordx4 v[210:213], v222, s[52:53] offset:64 nt
	global_load_dwordx4 v[214:217], v222, s[52:53] offset:512 nt
	global_load_dwordx4 v[218:221], v222, s[52:53] offset:576 nt
	s_add_u32 s52, s52, 0x20000
	s_addc_u32 s53, s53, 0
	global_store_dwordx4 v222, v[92:95], s[54:55]
	global_store_dwordx4 v222, v[88:91], s[54:55] offset:64
	global_store_dwordx4 v222, v[84:87], s[54:55] offset:512
	global_store_dwordx4 v222, v[80:83], s[54:55] offset:576
	s_add_u32 s54, s54, 0x20000
	s_addc_u32 s55, s55, 0
	v_mul_f32_e32 v140, v92, v158
	v_mul_f32_e32 v141, v93, v159
	v_mul_f32_e32 v142, v94, v160
	v_mul_f32_e32 v143, v95, v161
	v_cvt_pk_bf16_f32 v224, v140, v141
	v_cvt_pk_bf16_f32 v225, v142, v143
	global_store_dwordx2 v223, v[224:225], s[56:57]
	v_mul_f32_e32 v140, v88, v162
	v_mul_f32_e32 v141, v89, v163
	v_mul_f32_e32 v142, v90, v164
	v_mul_f32_e32 v143, v91, v165
	v_cvt_pk_bf16_f32 v226, v140, v141
	v_cvt_pk_bf16_f32 v227, v142, v143
	global_store_dwordx2 v223, v[226:227], s[56:57] offset:32
	v_mul_f32_e32 v140, v84, v166
	v_mul_f32_e32 v141, v85, v167
	v_mul_f32_e32 v142, v86, v168
	v_mul_f32_e32 v143, v87, v169
	v_cvt_pk_bf16_f32 v228, v140, v141
	v_cvt_pk_bf16_f32 v229, v142, v143
	global_store_dwordx2 v223, v[228:229], s[56:57] offset:256
	v_mul_f32_e32 v140, v80, v170
	v_mul_f32_e32 v141, v81, v171
	v_mul_f32_e32 v142, v82, v172
	v_mul_f32_e32 v143, v83, v173
	v_cvt_pk_bf16_f32 v230, v140, v141
	v_cvt_pk_bf16_f32 v231, v142, v143
	global_store_dwordx2 v223, v[230:231], s[56:57] offset:288
	s_add_u32 s56, s56, 0x10000
	s_addc_u32 s57, s57, 0
	v_mul_f32_e32 v140, v93, v93
	v_mul_f32_e32 v141, v95, v95
	v_fmac_f32_e32 v140, v92, v92
	v_fmac_f32_e32 v141, v94, v94
	v_add_f32_e32 v142, v140, v141
	v_mul_f32_e32 v140, v89, v89
	v_mul_f32_e32 v141, v91, v91
	v_fmac_f32_e32 v140, v88, v88
	v_fmac_f32_e32 v141, v90, v90
	v_add_f32_e32 v140, v140, v141
	v_add_f32_e32 v142, v142, v140
	v_mul_f32_e32 v140, v85, v85
	v_mul_f32_e32 v141, v87, v87
	v_fmac_f32_e32 v140, v84, v84
	v_fmac_f32_e32 v141, v86, v86
	v_add_f32_e32 v140, v140, v141
	v_add_f32_e32 v142, v142, v140
	v_mul_f32_e32 v140, v81, v81
	v_mul_f32_e32 v141, v83, v83
	v_fmac_f32_e32 v140, v80, v80
	v_fmac_f32_e32 v141, v82, v82
	v_add_f32_e32 v140, v140, v141
	v_add_f32_e32 v142, v142, v140
	v_mov_b32_e32 v80, v142
	s_waitcnt vmcnt(32)
; __device__ __forceinline__ unsigned cvt_pk_bf16(float lo, float hi) { unsigned r; asm volatile("v_cvt_pk_bf16_f32 %0, %1, %2" : "=v"(r) : "v"(lo), "v"(hi)); return r; }
;     __device__ __forceinline__ void operator()(const f32x4 (&acc)[2][2][4][2], const Unit& u, int wr, int wc, int fr, int fq) const {
;     ...
;             for (int m = 0; m < 4; ++m) { const int row = row0 + ai * HALF + m * 16; const size_t ro = (size_t)row * 2048 + col0; float ss = 0.f;
; #pragma unroll
;                 for (int bj = 0; bj < 2; ++bj)
; #pragma unroll
;                     for (int n = 0; n < 2; ++n) { const size_t off = ro + bj * HALF + n * 16; const f32x4 hv = *(const f32x4*)(R + off) + acc[ai][bj][m][n];
;                         *(f32x4*)(H + off) = hv; ss += (hv[0] * hv[0] + hv[1] * hv[1]) + (hv[2] * hv[2] + hv[3] * hv[3]);
;                         if (WITH_A5) { const f32x4 gv = *(const f32x4*)(gm + col0 + bj * HALF + n * 16); u32x2 w; w.x = cvt_pk_bf16(hv[0] * gv[0], hv[1] * gv[1]); w.y = cvt_pk_bf16(hv[2] * gv[2], hv[3] * gv[3]); *(u32x2*)(a5 + off) = w; } }
	v_pk_add_f32 v[76:77], v[76:77], v[174:175]
	v_pk_add_f32 v[78:79], v[78:79], v[176:177]
	v_pk_add_f32 v[72:73], v[72:73], v[178:179]
	v_pk_add_f32 v[74:75], v[74:75], v[180:181]
	v_pk_add_f32 v[68:69], v[68:69], v[182:183]
	v_pk_add_f32 v[70:71], v[70:71], v[184:185]
	v_pk_add_f32 v[64:65], v[64:65], v[186:187]
	v_pk_add_f32 v[66:67], v[66:67], v[188:189]
	global_load_dwordx4 v[174:177], v222, s[52:53] nt
	global_load_dwordx4 v[178:181], v222, s[52:53] offset:64 nt
	global_load_dwordx4 v[182:185], v222, s[52:53] offset:512 nt
	global_load_dwordx4 v[186:189], v222, s[52:53] offset:576 nt
	s_add_u32 s52, s52, 0x20000
	s_addc_u32 s53, s53, 0
	global_store_dwordx4 v222, v[76:79], s[54:55]
	global_store_dwordx4 v222, v[72:75], s[54:55] offset:64
	global_store_dwordx4 v222, v[68:71], s[54:55] offset:512
	global_store_dwordx4 v222, v[64:67], s[54:55] offset:576
	s_add_u32 s54, s54, 0xa0000
	s_addc_u32 s55, s55, 0
	v_mul_f32_e32 v140, v76, v158
	v_mul_f32_e32 v141, v77, v159
	v_mul_f32_e32 v142, v78, v160
	v_mul_f32_e32 v143, v79, v161
	v_cvt_pk_bf16_f32 v224, v140, v141
	v_cvt_pk_bf16_f32 v225, v142, v143
	global_store_dwordx2 v223, v[224:225], s[56:57]
	v_mul_f32_e32 v140, v72, v162
	v_mul_f32_e32 v141, v73, v163
	v_mul_f32_e32 v142, v74, v164
	v_mul_f32_e32 v143, v75, v165
	v_cvt_pk_bf16_f32 v226, v140, v141
	v_cvt_pk_bf16_f32 v227, v142, v143
	global_store_dwordx2 v223, v[226:227], s[56:57] offset:32
	v_mul_f32_e32 v140, v68, v166
	v_mul_f32_e32 v141, v69, v167
	v_mul_f32_e32 v142, v70, v168
	v_mul_f32_e32 v143, v71, v169
	v_cvt_pk_bf16_f32 v228, v140, v141
	v_cvt_pk_bf16_f32 v229, v142, v143
	global_store_dwordx2 v223, v[228:229], s[56:57] offset:256
	v_mul_f32_e32 v140, v64, v170
	v_mul_f32_e32 v141, v65, v171
	v_mul_f32_e32 v142, v66, v172
	v_mul_f32_e32 v143, v67, v173
	v_cvt_pk_bf16_f32 v230, v140, v141
	v_cvt_pk_bf16_f32 v231, v142, v143
	global_store_dwordx2 v223, v[230:231], s[56:57] offset:288
	s_add_u32 s56, s56, 0x50000
	s_addc_u32 s57, s57, 0
	v_mul_f32_e32 v140, v77, v77
	v_mul_f32_e32 v141, v79, v79
	v_fmac_f32_e32 v140, v76, v76
	v_fmac_f32_e32 v141, v78, v78
	v_add_f32_e32 v142, v140, v141
	v_mul_f32_e32 v140, v73, v73
	v_mul_f32_e32 v141, v75, v75
	v_fmac_f32_e32 v140, v72, v72
	v_fmac_f32_e32 v141, v74, v74
	v_add_f32_e32 v140, v140, v141
	v_add_f32_e32 v142, v142, v140
	v_mul_f32_e32 v140, v69, v69
	v_mul_f32_e32 v141, v71, v71
	v_fmac_f32_e32 v140, v68, v68
	v_fmac_f32_e32 v141, v70, v70
	v_add_f32_e32 v140, v140, v141
	v_add_f32_e32 v142, v142, v140
	v_mul_f32_e32 v140, v65, v65
	v_mul_f32_e32 v141, v67, v67
	v_fmac_f32_e32 v140, v64, v64
	v_fmac_f32_e32 v141, v66, v66
	v_add_f32_e32 v140, v140, v141
	v_add_f32_e32 v142, v142, v140
	v_mov_b32_e32 v64, v142
	s_waitcnt vmcnt(32)
	v_pk_add_f32 v[60:61], v[60:61], v[190:191]
	v_pk_add_f32 v[62:63], v[62:63], v[192:193]
	v_pk_add_f32 v[56:57], v[56:57], v[194:195]
	v_pk_add_f32 v[58:59], v[58:59], v[196:197]
	v_pk_add_f32 v[52:53], v[52:53], v[198:199]
	v_pk_add_f32 v[54:55], v[54:55], v[200:201]
	v_pk_add_f32 v[48:49], v[48:49], v[202:203]
	v_pk_add_f32 v[50:51], v[50:51], v[204:205]
	global_load_dwordx4 v[190:193], v222, s[52:53] nt
	global_load_dwordx4 v[194:197], v222, s[52:53] offset:64 nt
	global_load_dwordx4 v[198:201], v222, s[52:53] offset:512 nt
	global_load_dwordx4 v[202:205], v222, s[52:53] offset:576 nt
	global_store_dwordx4 v222, v[60:63], s[54:55]
	global_store_dwordx4 v222, v[56:59], s[54:55] offset:64
	global_store_dwordx4 v222, v[52:55], s[54:55] offset:512
	global_store_dwordx4 v222, v[48:51], s[54:55] offset:576
	s_add_u32 s54, s54, 0x20000
	s_addc_u32 s55, s55, 0
	v_mul_f32_e32 v140, v60, v158
	v_mul_f32_e32 v141, v61, v159
	v_mul_f32_e32 v142, v62, v160
	v_mul_f32_e32 v143, v63, v161
	v_cvt_pk_bf16_f32 v224, v140, v141
	v_cvt_pk_bf16_f32 v225, v142, v143
	global_store_dwordx2 v223, v[224:225], s[56:57]
	v_mul_f32_e32 v140, v56, v162
	v_mul_f32_e32 v141, v57, v163
	v_mul_f32_e32 v142, v58, v164
	v_mul_f32_e32 v143, v59, v165
	v_cvt_pk_bf16_f32 v226, v140, v141
	v_cvt_pk_bf16_f32 v227, v142, v143
	global_store_dwordx2 v223, v[226:227], s[56:57] offset:32
	v_mul_f32_e32 v140, v52, v166
	v_mul_f32_e32 v141, v53, v167
	v_mul_f32_e32 v142, v54, v168
	v_mul_f32_e32 v143, v55, v169
	v_cvt_pk_bf16_f32 v228, v140, v141
	v_cvt_pk_bf16_f32 v229, v142, v143
	global_store_dwordx2 v223, v[228:229], s[56:57] offset:256
	v_mul_f32_e32 v140, v48, v170
	v_mul_f32_e32 v141, v49, v171
	v_mul_f32_e32 v142, v50, v172
	v_mul_f32_e32 v143, v51, v173
	v_cvt_pk_bf16_f32 v230, v140, v141
	v_cvt_pk_bf16_f32 v231, v142, v143
	global_store_dwordx2 v223, v[230:231], s[56:57] offset:288
	s_add_u32 s56, s56, 0x10000
	s_addc_u32 s57, s57, 0
	v_mul_f32_e32 v140, v61, v61
	v_mul_f32_e32 v141, v63, v63
	v_fmac_f32_e32 v140, v60, v60
	v_fmac_f32_e32 v141, v62, v62
	v_add_f32_e32 v142, v140, v141
	v_mul_f32_e32 v140, v57, v57
	v_mul_f32_e32 v141, v59, v59
	v_fmac_f32_e32 v140, v56, v56
	v_fmac_f32_e32 v141, v58, v58
	v_add_f32_e32 v140, v140, v141
	v_add_f32_e32 v142, v142, v140
	v_mul_f32_e32 v140, v53, v53
	v_mul_f32_e32 v141, v55, v55
	v_fmac_f32_e32 v140, v52, v52
	v_fmac_f32_e32 v141, v54, v54
	v_add_f32_e32 v140, v140, v141
	v_add_f32_e32 v142, v142, v140
	v_mul_f32_e32 v140, v49, v49
	v_mul_f32_e32 v141, v51, v51
	v_fmac_f32_e32 v140, v48, v48
	v_fmac_f32_e32 v141, v50, v50
	v_add_f32_e32 v140, v140, v141
	v_add_f32_e32 v142, v142, v140
	v_mov_b32_e32 v48, v142
	s_waitcnt vmcnt(32)
; __device__ __forceinline__ unsigned cvt_pk_bf16(float lo, float hi) { unsigned r; asm volatile("v_cvt_pk_bf16_f32 %0, %1, %2" : "=v"(r) : "v"(lo), "v"(hi)); return r; }
;     __device__ __forceinline__ void operator()(const f32x4 (&acc)[2][2][4][2], const Unit& u, int wr, int wc, int fr, int fq) const {
;     ...
;             for (int m = 0; m < 4; ++m) { const int row = row0 + ai * HALF + m * 16; const size_t ro = (size_t)row * 2048 + col0; float ss = 0.f;
; #pragma unroll
;                 for (int bj = 0; bj < 2; ++bj)
; #pragma unroll
;                     for (int n = 0; n < 2; ++n) { const size_t off = ro + bj * HALF + n * 16; const f32x4 hv = *(const f32x4*)(R + off) + acc[ai][bj][m][n];
;                         *(f32x4*)(H + off) = hv; ss += (hv[0] * hv[0] + hv[1] * hv[1]) + (hv[2] * hv[2] + hv[3] * hv[3]);
;                         if (WITH_A5) { const f32x4 gv = *(const f32x4*)(gm + col0 + bj * HALF + n * 16); u32x2 w; w.x = cvt_pk_bf16(hv[0] * gv[0], hv[1] * gv[1]); w.y = cvt_pk_bf16(hv[2] * gv[2], hv[3] * gv[3]); *(u32x2*)(a5 + off) = w; } }
	v_pk_add_f32 v[44:45], v[44:45], v[206:207]
	v_pk_add_f32 v[46:47], v[46:47], v[208:209]
	v_pk_add_f32 v[40:41], v[40:41], v[210:211]
	v_pk_add_f32 v[42:43], v[42:43], v[212:213]
	v_pk_add_f32 v[36:37], v[36:37], v[214:215]
	v_pk_add_f32 v[38:39], v[38:39], v[216:217]
	v_pk_add_f32 v[32:33], v[32:33], v[218:219]
	v_pk_add_f32 v[34:35], v[34:35], v[220:221]
	global_store_dwordx4 v222, v[44:47], s[54:55]
	global_store_dwordx4 v222, v[40:43], s[54:55] offset:64
	global_store_dwordx4 v222, v[36:39], s[54:55] offset:512
	global_store_dwordx4 v222, v[32:35], s[54:55] offset:576
	s_add_u32 s54, s54, 0x20000
	s_addc_u32 s55, s55, 0
	v_mul_f32_e32 v140, v44, v158
	v_mul_f32_e32 v141, v45, v159
	v_mul_f32_e32 v142, v46, v160
	v_mul_f32_e32 v143, v47, v161
	v_cvt_pk_bf16_f32 v224, v140, v141
	v_cvt_pk_bf16_f32 v225, v142, v143
	global_store_dwordx2 v223, v[224:225], s[56:57]
	v_mul_f32_e32 v140, v40, v162
	v_mul_f32_e32 v141, v41, v163
	v_mul_f32_e32 v142, v42, v164
	v_mul_f32_e32 v143, v43, v165
	v_cvt_pk_bf16_f32 v226, v140, v141
	v_cvt_pk_bf16_f32 v227, v142, v143
	global_store_dwordx2 v223, v[226:227], s[56:57] offset:32
	v_mul_f32_e32 v140, v36, v166
	v_mul_f32_e32 v141, v37, v167
	v_mul_f32_e32 v142, v38, v168
	v_mul_f32_e32 v143, v39, v169
	v_cvt_pk_bf16_f32 v228, v140, v141
	v_cvt_pk_bf16_f32 v229, v142, v143
	global_store_dwordx2 v223, v[228:229], s[56:57] offset:256
	v_mul_f32_e32 v140, v32, v170
	v_mul_f32_e32 v141, v33, v171
	v_mul_f32_e32 v142, v34, v172
	v_mul_f32_e32 v143, v35, v173
	v_cvt_pk_bf16_f32 v230, v140, v141
	v_cvt_pk_bf16_f32 v231, v142, v143
	global_store_dwordx2 v223, v[230:231], s[56:57] offset:288
	s_add_u32 s56, s56, 0x10000
	s_addc_u32 s57, s57, 0
	v_mul_f32_e32 v140, v45, v45
	v_mul_f32_e32 v141, v47, v47
	v_fmac_f32_e32 v140, v44, v44
	v_fmac_f32_e32 v141, v46, v46
	v_add_f32_e32 v142, v140, v141
	v_mul_f32_e32 v140, v41, v41
	v_mul_f32_e32 v141, v43, v43
	v_fmac_f32_e32 v140, v40, v40
	v_fmac_f32_e32 v141, v42, v42
	v_add_f32_e32 v140, v140, v141
	v_add_f32_e32 v142, v142, v140
	v_mul_f32_e32 v140, v37, v37
	v_mul_f32_e32 v141, v39, v39
	v_fmac_f32_e32 v140, v36, v36
	v_fmac_f32_e32 v141, v38, v38
	v_add_f32_e32 v140, v140, v141
	v_add_f32_e32 v142, v142, v140
	v_mul_f32_e32 v140, v33, v33
	v_mul_f32_e32 v141, v35, v35
	v_fmac_f32_e32 v140, v32, v32
	v_fmac_f32_e32 v141, v34, v34
	v_add_f32_e32 v140, v140, v141
	v_add_f32_e32 v142, v142, v140
	v_mov_b32_e32 v32, v142
	s_waitcnt vmcnt(28)
	v_pk_add_f32 v[28:29], v[28:29], v[174:175]
	v_pk_add_f32 v[30:31], v[30:31], v[176:177]
	v_pk_add_f32 v[24:25], v[24:25], v[178:179]
	v_pk_add_f32 v[26:27], v[26:27], v[180:181]
	v_pk_add_f32 v[20:21], v[20:21], v[182:183]
	v_pk_add_f32 v[22:23], v[22:23], v[184:185]
	v_pk_add_f32 v[16:17], v[16:17], v[186:187]
	v_pk_add_f32 v[18:19], v[18:19], v[188:189]
	global_store_dwordx4 v222, v[28:31], s[54:55]
	global_store_dwordx4 v222, v[24:27], s[54:55] offset:64
	global_store_dwordx4 v222, v[20:23], s[54:55] offset:512
	global_store_dwordx4 v222, v[16:19], s[54:55] offset:576
	s_add_u32 s54, s54, 0x20000
	s_addc_u32 s55, s55, 0
	v_mul_f32_e32 v140, v28, v158
	v_mul_f32_e32 v141, v29, v159
	v_mul_f32_e32 v142, v30, v160
	v_mul_f32_e32 v143, v31, v161
	v_cvt_pk_bf16_f32 v224, v140, v141
	v_cvt_pk_bf16_f32 v225, v142, v143
	global_store_dwordx2 v223, v[224:225], s[56:57]
	v_mul_f32_e32 v140, v24, v162
	v_mul_f32_e32 v141, v25, v163
	v_mul_f32_e32 v142, v26, v164
	v_mul_f32_e32 v143, v27, v165
	v_cvt_pk_bf16_f32 v226, v140, v141
	v_cvt_pk_bf16_f32 v227, v142, v143
	global_store_dwordx2 v223, v[226:227], s[56:57] offset:32
	v_mul_f32_e32 v140, v20, v166
	v_mul_f32_e32 v141, v21, v167
	v_mul_f32_e32 v142, v22, v168
	v_mul_f32_e32 v143, v23, v169
	v_cvt_pk_bf16_f32 v228, v140, v141
	v_cvt_pk_bf16_f32 v229, v142, v143
	global_store_dwordx2 v223, v[228:229], s[56:57] offset:256
	v_mul_f32_e32 v140, v16, v170
	v_mul_f32_e32 v141, v17, v171
	v_mul_f32_e32 v142, v18, v172
	v_mul_f32_e32 v143, v19, v173
	v_cvt_pk_bf16_f32 v230, v140, v141
	v_cvt_pk_bf16_f32 v231, v142, v143
	global_store_dwordx2 v223, v[230:231], s[56:57] offset:288
	s_add_u32 s56, s56, 0x10000
	s_addc_u32 s57, s57, 0
	v_mul_f32_e32 v140, v29, v29
	v_mul_f32_e32 v141, v31, v31
	v_fmac_f32_e32 v140, v28, v28
	v_fmac_f32_e32 v141, v30, v30
	v_add_f32_e32 v142, v140, v141
	v_mul_f32_e32 v140, v25, v25
	v_mul_f32_e32 v141, v27, v27
	v_fmac_f32_e32 v140, v24, v24
	v_fmac_f32_e32 v141, v26, v26
	v_add_f32_e32 v140, v140, v141
	v_add_f32_e32 v142, v142, v140
	v_mul_f32_e32 v140, v21, v21
	v_mul_f32_e32 v141, v23, v23
	v_fmac_f32_e32 v140, v20, v20
	v_fmac_f32_e32 v141, v22, v22
	v_add_f32_e32 v140, v140, v141
	v_add_f32_e32 v142, v142, v140
	v_mul_f32_e32 v140, v17, v17
	v_mul_f32_e32 v141, v19, v19
	v_fmac_f32_e32 v140, v16, v16
	v_fmac_f32_e32 v141, v18, v18
	v_add_f32_e32 v140, v140, v141
	v_add_f32_e32 v142, v142, v140
	v_mov_b32_e32 v16, v142
	s_waitcnt vmcnt(24)
; __device__ __forceinline__ unsigned cvt_pk_bf16(float lo, float hi) { unsigned r; asm volatile("v_cvt_pk_bf16_f32 %0, %1, %2" : "=v"(r) : "v"(lo), "v"(hi)); return r; }
; #define PG8_BAR __builtin_amdgcn_s_barrier()
;     __device__ __forceinline__ void operator()(const f32x4 (&acc)[2][2][4][2], const Unit& u, int wr, int wc, int fr, int fq) const {
;     ...
;                     for (int n = 0; n < 2; ++n) { const size_t off = ro + bj * HALF + n * 16; const f32x4 hv = *(const f32x4*)(R + off) + acc[ai][bj][m][n];
;                         *(f32x4*)(H + off) = hv; ss += (hv[0] * hv[0] + hv[1] * hv[1]) + (hv[2] * hv[2] + hv[3] * hv[3]);
;                         if (WITH_A5) { const f32x4 gv = *(const f32x4*)(gm + col0 + bj * HALF + n * 16); u32x2 w; w.x = cvt_pk_bf16(hv[0] * gv[0], hv[1] * gv[1]); w.y = cvt_pk_bf16(hv[2] * gv[2], hv[3] * gv[3]); *(u32x2*)(a5 + off) = w; } }
;                 ss += __shfl_xor(ss, 16); ss += __shfl_xor(ss, 32);
;                 if (fq == 0) atomicAdd(rowss + row, ss); }
; template <class Epi, class Sched, bool ALIGN_EPI = false, bool SP2 = false>
; __device__ __forceinline__ void gemm_phase(PG8_LAS unsigned char* lds, const Gemm g, const Sched& S, const Epi& E) {
;     ...
;         if constexpr (!Epi::AFTER_DRAIN) { E(acc, cur, wr, wc, fr, fq); S.done(cur); }
;         if (!has_next) break;
; #pragma unroll
;         for (int a = 0; a < 2; ++a)
; #pragma unroll
;             for (int b = 0; b < 2; ++b)
; #pragma unroll
;                 for (int m = 0; m < 4; ++m)
; #pragma unroll
;                     for (int n = 0; n < 2; ++n) acc[a][b][m][n] = (f32x4){0.f, 0.f, 0.f, 0.f};
;         cur = nxt; cA = nA; cB = nB; ++ui;
;         if constexpr (ALIGN_EPI) { if (wr == 1) PG8_BAR; }
	v_pk_add_f32 v[12:13], v[12:13], v[190:191]
	v_pk_add_f32 v[14:15], v[14:15], v[192:193]
	v_pk_add_f32 v[8:9], v[8:9], v[194:195]
	v_pk_add_f32 v[10:11], v[10:11], v[196:197]
	v_pk_add_f32 v[4:5], v[4:5], v[198:199]
	v_pk_add_f32 v[6:7], v[6:7], v[200:201]
	v_pk_add_f32 v[0:1], v[0:1], v[202:203]
	v_pk_add_f32 v[2:3], v[2:3], v[204:205]
	global_store_dwordx4 v222, v[12:15], s[54:55]
	global_store_dwordx4 v222, v[8:11], s[54:55] offset:64
	global_store_dwordx4 v222, v[4:7], s[54:55] offset:512
	global_store_dwordx4 v222, v[0:3], s[54:55] offset:576
	v_mul_f32_e32 v140, v12, v158
	v_mul_f32_e32 v141, v13, v159
	v_mul_f32_e32 v142, v14, v160
	v_mul_f32_e32 v143, v15, v161
	v_cvt_pk_bf16_f32 v224, v140, v141
	v_cvt_pk_bf16_f32 v225, v142, v143
	global_store_dwordx2 v223, v[224:225], s[56:57]
	v_mul_f32_e32 v140, v8, v162
	v_mul_f32_e32 v141, v9, v163
	v_mul_f32_e32 v142, v10, v164
	v_mul_f32_e32 v143, v11, v165
	v_cvt_pk_bf16_f32 v226, v140, v141
	v_cvt_pk_bf16_f32 v227, v142, v143
	global_store_dwordx2 v223, v[226:227], s[56:57] offset:32
	v_mul_f32_e32 v140, v4, v166
	v_mul_f32_e32 v141, v5, v167
	v_mul_f32_e32 v142, v6, v168
	v_mul_f32_e32 v143, v7, v169
	v_cvt_pk_bf16_f32 v228, v140, v141
	v_cvt_pk_bf16_f32 v229, v142, v143
	global_store_dwordx2 v223, v[228:229], s[56:57] offset:256
	v_mul_f32_e32 v140, v0, v170
	v_mul_f32_e32 v141, v1, v171
	v_mul_f32_e32 v142, v2, v172
	v_mul_f32_e32 v143, v3, v173
	v_cvt_pk_bf16_f32 v230, v140, v141
	v_cvt_pk_bf16_f32 v231, v142, v143
	global_store_dwordx2 v223, v[230:231], s[56:57] offset:288
	v_mul_f32_e32 v140, v13, v13
	v_mul_f32_e32 v141, v15, v15
	v_fmac_f32_e32 v140, v12, v12
	v_fmac_f32_e32 v141, v14, v14
	v_add_f32_e32 v142, v140, v141
	v_mul_f32_e32 v140, v9, v9
	v_mul_f32_e32 v141, v11, v11
	v_fmac_f32_e32 v140, v8, v8
	v_fmac_f32_e32 v141, v10, v10
	v_add_f32_e32 v140, v140, v141
	v_add_f32_e32 v142, v142, v140
	v_mul_f32_e32 v140, v5, v5
	v_mul_f32_e32 v141, v7, v7
	v_fmac_f32_e32 v140, v4, v4
	v_fmac_f32_e32 v141, v6, v6
	v_add_f32_e32 v140, v140, v141
	v_add_f32_e32 v142, v142, v140
	v_mul_f32_e32 v140, v1, v1
	v_mul_f32_e32 v141, v3, v3
	v_fmac_f32_e32 v140, v0, v0
	v_fmac_f32_e32 v141, v2, v2
	v_add_f32_e32 v140, v140, v141
	v_add_f32_e32 v142, v142, v140
	v_mov_b32_e32 v0, v142
	ds_bpermute_b32 v113, v144, v112
	ds_bpermute_b32 v97, v144, v96
	ds_bpermute_b32 v81, v144, v80
	ds_bpermute_b32 v65, v144, v64
	ds_bpermute_b32 v49, v144, v48
	ds_bpermute_b32 v33, v144, v32
	ds_bpermute_b32 v17, v144, v16
	ds_bpermute_b32 v1, v144, v0
	s_waitcnt lgkmcnt(0)
	v_add_f32_e32 v112, v112, v113
	v_add_f32_e32 v96, v96, v97
	v_add_f32_e32 v80, v80, v81
	v_add_f32_e32 v64, v64, v65
	v_add_f32_e32 v48, v48, v49
	v_add_f32_e32 v32, v32, v33
	v_add_f32_e32 v16, v16, v17
	v_add_f32_e32 v0, v0, v1
	ds_bpermute_b32 v113, v145, v112
	ds_bpermute_b32 v97, v145, v96
	ds_bpermute_b32 v81, v145, v80
	ds_bpermute_b32 v65, v145, v64
	ds_bpermute_b32 v49, v145, v48
	ds_bpermute_b32 v33, v145, v32
	ds_bpermute_b32 v17, v145, v16
	ds_bpermute_b32 v1, v145, v0
	s_waitcnt lgkmcnt(0)
	v_add_f32_e32 v112, v112, v113
	v_add_f32_e32 v96, v96, v97
	v_add_f32_e32 v80, v80, v81
	v_add_f32_e32 v64, v64, v65
	v_add_f32_e32 v48, v48, v49
	v_add_f32_e32 v32, v32, v33
	v_add_f32_e32 v16, v16, v17
	v_add_f32_e32 v0, v0, v1
	s_and_saveexec_b64 s[2:3], s[0:1]
	global_atomic_add_f32 v153, v112, s[58:59]
	global_atomic_add_f32 v153, v96, s[58:59] offset:64
	global_atomic_add_f32 v153, v80, s[58:59] offset:128
	global_atomic_add_f32 v153, v64, s[58:59] offset:192
	global_atomic_add_f32 v153, v48, s[58:59] offset:512
	global_atomic_add_f32 v153, v32, s[58:59] offset:576
	global_atomic_add_f32 v153, v16, s[58:59] offset:640
	global_atomic_add_f32 v153, v0, s[58:59] offset:704
	s_or_b64 exec, exec, s[2:3]
	s_andn2_b64 vcc, exec, s[4:5]
	s_mov_b64 s[2:3], -1
	s_cbranch_vccnz .LBB0_725
	s_andn2_b64 vcc, exec, s[8:9]
	s_cbranch_vccnz .LBB0_724
	s_barrier
	s_branch .LBB0_724

;     __device__ __forceinline__ void operator()(const f32x4 (&acc)[2][2][4][2], const Unit& u, int wr, int wc, int fr, int fq) const {
;         const int row0 = u.pm * BM + wr * 64 + fr, col0 = u.pn * BM + wc * 32 + 4 * fq;
; #pragma unroll
;         for (int ai = 0; ai < 2; ++ai)
; #pragma unroll
;             for (int m = 0; m < 4; ++m) { const int row = row0 + ai * HALF + m * 16; const size_t ro = (size_t)row * 2048 + col0; float ss = 0.f;
; #pragma unroll
;                 for (int bj = 0; bj < 2; ++bj)
; #pragma unroll
;                     for (int n = 0; n < 2; ++n) { const size_t off = ro + bj * HALF + n * 16; const f32x4 hv = *(const f32x4*)(R + off) + acc[ai][bj][m][n];
;                         *(f32x4*)(H + off) = hv; ss += (hv[0] * hv[0] + hv[1] * hv[1]) + (hv[2] * hv[2] + hv[3] * hv[3]);
.LBB0_904:
	v_lshlrev_b32_e32 v222, 13, v144
	v_lshl_add_u32 v222, v146, 2, v222
	v_lshlrev_b32_e32 v153, 2, v144
	v_xor_b32_e32 v151, 16, v150
	v_xor_b32_e32 v152, 32, v150
	v_lshlrev_b32_e32 v151, 2, v151
	v_lshlrev_b32_e32 v152, 2, v152
	s_lshl_b32 s62, s22, 21
	s_lshl_b32 s63, s24, 10
	s_add_u32 s62, s62, s63
	s_add_u32 s52, s86, s62
	s_addc_u32 s53, s87, 0
	s_add_u32 s54, s86, s62
	s_addc_u32 s55, s87, 0
	s_lshl_b32 s63, s22, 10
	s_add_u32 s58, s10, s63
	s_addc_u32 s59, s11, 0
	global_load_dwordx4 v[174:177], v222, s[52:53] nt
	global_load_dwordx4 v[178:181], v222, s[52:53] offset:64 nt
	global_load_dwordx4 v[182:185], v222, s[52:53] offset:512 nt
	global_load_dwordx4 v[186:189], v222, s[52:53] offset:576 nt
	s_add_u32 s52, s52, 0x20000
	s_addc_u32 s53, s53, 0
	global_load_dwordx4 v[190:193], v222, s[52:53] nt
	global_load_dwordx4 v[194:197], v222, s[52:53] offset:64 nt
	global_load_dwordx4 v[198:201], v222, s[52:53] offset:512 nt
	global_load_dwordx4 v[202:205], v222, s[52:53] offset:576 nt
	s_add_u32 s52, s52, 0x20000
	s_addc_u32 s53, s53, 0
	global_load_dwordx4 v[206:209], v222, s[52:53] nt
	global_load_dwordx4 v[210:213], v222, s[52:53] offset:64 nt
	global_load_dwordx4 v[214:217], v222, s[52:53] offset:512 nt
	global_load_dwordx4 v[218:221], v222, s[52:53] offset:576 nt
	s_add_u32 s52, s52, 0x20000
	s_addc_u32 s53, s53, 0
	s_waitcnt vmcnt(8)
	v_pk_add_f32 v[124:125], v[124:125], v[174:175]
	v_pk_add_f32 v[126:127], v[126:127], v[176:177]
	v_pk_add_f32 v[120:121], v[120:121], v[178:179]
	v_pk_add_f32 v[122:123], v[122:123], v[180:181]
	v_pk_add_f32 v[116:117], v[116:117], v[182:183]
	v_pk_add_f32 v[118:119], v[118:119], v[184:185]
	v_pk_add_f32 v[112:113], v[112:113], v[186:187]
	v_pk_add_f32 v[114:115], v[114:115], v[188:189]
	global_load_dwordx4 v[174:177], v222, s[52:53] nt
	global_load_dwordx4 v[178:181], v222, s[52:53] offset:64 nt
	global_load_dwordx4 v[182:185], v222, s[52:53] offset:512 nt
	global_load_dwordx4 v[186:189], v222, s[52:53] offset:576 nt
	s_add_u32 s52, s52, 0xa0000
	s_addc_u32 s53, s53, 0
	global_store_dwordx4 v222, v[124:127], s[54:55]
	global_store_dwordx4 v222, v[120:123], s[54:55] offset:64
	global_store_dwordx4 v222, v[116:119], s[54:55] offset:512
	global_store_dwordx4 v222, v[112:115], s[54:55] offset:576
	s_add_u32 s54, s54, 0x20000
	s_addc_u32 s55, s55, 0
	v_mul_f32_e32 v140, v125, v125
	v_mul_f32_e32 v141, v127, v127
	v_fmac_f32_e32 v140, v124, v124
	v_fmac_f32_e32 v141, v126, v126
	v_add_f32_e32 v142, v140, v141
	v_mul_f32_e32 v140, v121, v121
	v_mul_f32_e32 v141, v123, v123
	v_fmac_f32_e32 v140, v120, v120
	v_fmac_f32_e32 v141, v122, v122
	v_add_f32_e32 v140, v140, v141
	v_add_f32_e32 v142, v142, v140
	v_mul_f32_e32 v140, v117, v117
	v_mul_f32_e32 v141, v119, v119
	v_fmac_f32_e32 v140, v116, v116
	v_fmac_f32_e32 v141, v118, v118
	v_add_f32_e32 v140, v140, v141
	v_add_f32_e32 v142, v142, v140
	v_mul_f32_e32 v140, v113, v113
	v_mul_f32_e32 v141, v115, v115
	v_fmac_f32_e32 v140, v112, v112
	v_fmac_f32_e32 v141, v114, v114
	v_add_f32_e32 v140, v140, v141
	v_add_f32_e32 v142, v142, v140
	v_mov_b32_e32 v112, v142
	s_waitcnt vmcnt(12)
	v_pk_add_f32 v[108:109], v[108:109], v[190:191]
	v_pk_add_f32 v[110:111], v[110:111], v[192:193]
	v_pk_add_f32 v[104:105], v[104:105], v[194:195]
	v_pk_add_f32 v[106:107], v[106:107], v[196:197]
	v_pk_add_f32 v[100:101], v[100:101], v[198:199]
	v_pk_add_f32 v[102:103], v[102:103], v[200:201]
	v_pk_add_f32 v[96:97], v[96:97], v[202:203]
	v_pk_add_f32 v[98:99], v[98:99], v[204:205]
	global_load_dwordx4 v[190:193], v222, s[52:53] nt
	global_load_dwordx4 v[194:197], v222, s[52:53] offset:64 nt
	global_load_dwordx4 v[198:201], v222, s[52:53] offset:512 nt
	global_load_dwordx4 v[202:205], v222, s[52:53] offset:576 nt
	s_add_u32 s52, s52, 0x20000
	s_addc_u32 s53, s53, 0
	global_store_dwordx4 v222, v[108:111], s[54:55]
	global_store_dwordx4 v222, v[104:107], s[54:55] offset:64
	global_store_dwordx4 v222, v[100:103], s[54:55] offset:512
	global_store_dwordx4 v222, v[96:99], s[54:55] offset:576
	s_add_u32 s54, s54, 0x20000
	s_addc_u32 s55, s55, 0
	v_mul_f32_e32 v140, v109, v109
	v_mul_f32_e32 v141, v111, v111
	v_fmac_f32_e32 v140, v108, v108
	v_fmac_f32_e32 v141, v110, v110
	v_add_f32_e32 v142, v140, v141
	v_mul_f32_e32 v140, v105, v105
	v_mul_f32_e32 v141, v107, v107
	v_fmac_f32_e32 v140, v104, v104
	v_fmac_f32_e32 v141, v106, v106
	v_add_f32_e32 v140, v140, v141
	v_add_f32_e32 v142, v142, v140
	v_mul_f32_e32 v140, v101, v101
	v_mul_f32_e32 v141, v103, v103
	v_fmac_f32_e32 v140, v100, v100
	v_fmac_f32_e32 v141, v102, v102
	v_add_f32_e32 v140, v140, v141
	v_add_f32_e32 v142, v142, v140
	v_mul_f32_e32 v140, v97, v97
	v_mul_f32_e32 v141, v99, v99
	v_fmac_f32_e32 v140, v96, v96
	v_fmac_f32_e32 v141, v98, v98
	v_add_f32_e32 v140, v140, v141
	v_add_f32_e32 v142, v142, v140
	v_mov_b32_e32 v96, v142
	s_waitcnt vmcnt(16)
;     __device__ __forceinline__ void operator()(const f32x4 (&acc)[2][2][4][2], const Unit& u, int wr, int wc, int fr, int fq) const {
;     ...
;             for (int m = 0; m < 4; ++m) { const int row = row0 + ai * HALF + m * 16; const size_t ro = (size_t)row * 2048 + col0; float ss = 0.f;
; #pragma unroll
;                 for (int bj = 0; bj < 2; ++bj)
; #pragma unroll
;                     for (int n = 0; n < 2; ++n) { const size_t off = ro + bj * HALF + n * 16; const f32x4 hv = *(const f32x4*)(R + off) + acc[ai][bj][m][n];
;                         *(f32x4*)(H + off) = hv; ss += (hv[0] * hv[0] + hv[1] * hv[1]) + (hv[2] * hv[2] + hv[3] * hv[3]);
	v_pk_add_f32 v[92:93], v[92:93], v[206:207]
	v_pk_add_f32 v[94:95], v[94:95], v[208:209]
	v_pk_add_f32 v[88:89], v[88:89], v[210:211]
	v_pk_add_f32 v[90:91], v[90:91], v[212:213]
	v_pk_add_f32 v[84:85], v[84:85], v[214:215]
	v_pk_add_f32 v[86:87], v[86:87], v[216:217]
	v_pk_add_f32 v[80:81], v[80:81], v[218:219]
	v_pk_add_f32 v[82:83], v[82:83], v[220:221]
	global_load_dwordx4 v[206:209], v222, s[52:53] nt
	global_load_dwordx4 v[210:213], v222, s[52:53] offset:64 nt
	global_load_dwordx4 v[214:217], v222, s[52:53] offset:512 nt
	global_load_dwordx4 v[218:221], v222, s[52:53] offset:576 nt
	s_add_u32 s52, s52, 0x20000
	s_addc_u32 s53, s53, 0
	global_store_dwordx4 v222, v[92:95], s[54:55]
	global_store_dwordx4 v222, v[88:91], s[54:55] offset:64
	global_store_dwordx4 v222, v[84:87], s[54:55] offset:512
	global_store_dwordx4 v222, v[80:83], s[54:55] offset:576
	s_add_u32 s54, s54, 0x20000
	s_addc_u32 s55, s55, 0
	v_mul_f32_e32 v140, v93, v93
	v_mul_f32_e32 v141, v95, v95
	v_fmac_f32_e32 v140, v92, v92
	v_fmac_f32_e32 v141, v94, v94
	v_add_f32_e32 v142, v140, v141
	v_mul_f32_e32 v140, v89, v89
	v_mul_f32_e32 v141, v91, v91
	v_fmac_f32_e32 v140, v88, v88
	v_fmac_f32_e32 v141, v90, v90
	v_add_f32_e32 v140, v140, v141
	v_add_f32_e32 v142, v142, v140
	v_mul_f32_e32 v140, v85, v85
	v_mul_f32_e32 v141, v87, v87
	v_fmac_f32_e32 v140, v84, v84
	v_fmac_f32_e32 v141, v86, v86
	v_add_f32_e32 v140, v140, v141
	v_add_f32_e32 v142, v142, v140
	v_mul_f32_e32 v140, v81, v81
	v_mul_f32_e32 v141, v83, v83
	v_fmac_f32_e32 v140, v80, v80
	v_fmac_f32_e32 v141, v82, v82
	v_add_f32_e32 v140, v140, v141
	v_add_f32_e32 v142, v142, v140
	v_mov_b32_e32 v80, v142
	s_waitcnt vmcnt(20)
	v_pk_add_f32 v[76:77], v[76:77], v[174:175]
	v_pk_add_f32 v[78:79], v[78:79], v[176:177]
	v_pk_add_f32 v[72:73], v[72:73], v[178:179]
	v_pk_add_f32 v[74:75], v[74:75], v[180:181]
	v_pk_add_f32 v[68:69], v[68:69], v[182:183]
	v_pk_add_f32 v[70:71], v[70:71], v[184:185]
	v_pk_add_f32 v[64:65], v[64:65], v[186:187]
	v_pk_add_f32 v[66:67], v[66:67], v[188:189]
	global_load_dwordx4 v[174:177], v222, s[52:53] nt
	global_load_dwordx4 v[178:181], v222, s[52:53] offset:64 nt
	global_load_dwordx4 v[182:185], v222, s[52:53] offset:512 nt
	global_load_dwordx4 v[186:189], v222, s[52:53] offset:576 nt
	s_add_u32 s52, s52, 0x20000
	s_addc_u32 s53, s53, 0
	global_store_dwordx4 v222, v[76:79], s[54:55]
	global_store_dwordx4 v222, v[72:75], s[54:55] offset:64
	global_store_dwordx4 v222, v[68:71], s[54:55] offset:512
	global_store_dwordx4 v222, v[64:67], s[54:55] offset:576
	s_add_u32 s54, s54, 0xa0000
	s_addc_u32 s55, s55, 0
	v_mul_f32_e32 v140, v77, v77
	v_mul_f32_e32 v141, v79, v79
	v_fmac_f32_e32 v140, v76, v76
	v_fmac_f32_e32 v141, v78, v78
	v_add_f32_e32 v142, v140, v141
	v_mul_f32_e32 v140, v73, v73
	v_mul_f32_e32 v141, v75, v75
	v_fmac_f32_e32 v140, v72, v72
	v_fmac_f32_e32 v141, v74, v74
	v_add_f32_e32 v140, v140, v141
	v_add_f32_e32 v142, v142, v140
	v_mul_f32_e32 v140, v69, v69
	v_mul_f32_e32 v141, v71, v71
	v_fmac_f32_e32 v140, v68, v68
	v_fmac_f32_e32 v141, v70, v70
	v_add_f32_e32 v140, v140, v141
	v_add_f32_e32 v142, v142, v140
	v_mul_f32_e32 v140, v65, v65
	v_mul_f32_e32 v141, v67, v67
	v_fmac_f32_e32 v140, v64, v64
	v_fmac_f32_e32 v141, v66, v66
	v_add_f32_e32 v140, v140, v141
	v_add_f32_e32 v142, v142, v140
	v_mov_b32_e32 v64, v142
	s_waitcnt vmcnt(20)
	v_pk_add_f32 v[60:61], v[60:61], v[190:191]
	v_pk_add_f32 v[62:63], v[62:63], v[192:193]
	v_pk_add_f32 v[56:57], v[56:57], v[194:195]
	v_pk_add_f32 v[58:59], v[58:59], v[196:197]
	v_pk_add_f32 v[52:53], v[52:53], v[198:199]
	v_pk_add_f32 v[54:55], v[54:55], v[200:201]
	v_pk_add_f32 v[48:49], v[48:49], v[202:203]
	v_pk_add_f32 v[50:51], v[50:51], v[204:205]
	global_load_dwordx4 v[190:193], v222, s[52:53] nt
	global_load_dwordx4 v[194:197], v222, s[52:53] offset:64 nt
	global_load_dwordx4 v[198:201], v222, s[52:53] offset:512 nt
	global_load_dwordx4 v[202:205], v222, s[52:53] offset:576 nt
	global_store_dwordx4 v222, v[60:63], s[54:55]
	global_store_dwordx4 v222, v[56:59], s[54:55] offset:64
	global_store_dwordx4 v222, v[52:55], s[54:55] offset:512
	global_store_dwordx4 v222, v[48:51], s[54:55] offset:576
	s_add_u32 s54, s54, 0x20000
	s_addc_u32 s55, s55, 0
	v_mul_f32_e32 v140, v61, v61
	v_mul_f32_e32 v141, v63, v63
	v_fmac_f32_e32 v140, v60, v60
	v_fmac_f32_e32 v141, v62, v62
	v_add_f32_e32 v142, v140, v141
	v_mul_f32_e32 v140, v57, v57
	v_mul_f32_e32 v141, v59, v59
	v_fmac_f32_e32 v140, v56, v56
	v_fmac_f32_e32 v141, v58, v58
	v_add_f32_e32 v140, v140, v141
	v_add_f32_e32 v142, v142, v140
	v_mul_f32_e32 v140, v53, v53
	v_mul_f32_e32 v141, v55, v55
	v_fmac_f32_e32 v140, v52, v52
	v_fmac_f32_e32 v141, v54, v54
	v_add_f32_e32 v140, v140, v141
	v_add_f32_e32 v142, v142, v140
	v_mul_f32_e32 v140, v49, v49
	v_mul_f32_e32 v141, v51, v51
	v_fmac_f32_e32 v140, v48, v48
	v_fmac_f32_e32 v141, v50, v50
	v_add_f32_e32 v140, v140, v141
	v_add_f32_e32 v142, v142, v140
	v_mov_b32_e32 v48, v142
	s_waitcnt vmcnt(20)
; __device__ __forceinline__ unsigned cvt_pk_bf16(float lo, float hi) { unsigned r; asm volatile("v_cvt_pk_bf16_f32 %0, %1, %2" : "=v"(r) : "v"(lo), "v"(hi)); return r; }
;     __device__ __forceinline__ void operator()(const f32x4 (&acc)[2][2][4][2], const Unit& u, int wr, int wc, int fr, int fq) const {
;     ...
;             for (int m = 0; m < 4; ++m) { const int row = row0 + ai * HALF + m * 16; const size_t ro = (size_t)row * 2048 + col0; float ss = 0.f;
; #pragma unroll
;                 for (int bj = 0; bj < 2; ++bj)
; #pragma unroll
;                     for (int n = 0; n < 2; ++n) { const size_t off = ro + bj * HALF + n * 16; const f32x4 hv = *(const f32x4*)(R + off) + acc[ai][bj][m][n];
;                         *(f32x4*)(H + off) = hv; ss += (hv[0] * hv[0] + hv[1] * hv[1]) + (hv[2] * hv[2] + hv[3] * hv[3]);
;                         if (WITH_A5) { const f32x4 gv = *(const f32x4*)(gm + col0 + bj * HALF + n * 16); u32x2 w; w.x = cvt_pk_bf16(hv[0] * gv[0], hv[1] * gv[1]); w.y = cvt_pk_bf16(hv[2] * gv[2], hv[3] * gv[3]); *(u32x2*)(a5 + off) = w; } }
;                 ss += __shfl_xor(ss, 16); ss += __shfl_xor(ss, 32);
;                 if (fq == 0) atomicAdd(rowss + row, ss); }
	v_pk_add_f32 v[44:45], v[44:45], v[206:207]
	v_pk_add_f32 v[46:47], v[46:47], v[208:209]
	v_pk_add_f32 v[40:41], v[40:41], v[210:211]
	v_pk_add_f32 v[42:43], v[42:43], v[212:213]
	v_pk_add_f32 v[36:37], v[36:37], v[214:215]
	v_pk_add_f32 v[38:39], v[38:39], v[216:217]
	v_pk_add_f32 v[32:33], v[32:33], v[218:219]
	v_pk_add_f32 v[34:35], v[34:35], v[220:221]
	global_store_dwordx4 v222, v[44:47], s[54:55]
	global_store_dwordx4 v222, v[40:43], s[54:55] offset:64
	global_store_dwordx4 v222, v[36:39], s[54:55] offset:512
	global_store_dwordx4 v222, v[32:35], s[54:55] offset:576
	s_add_u32 s54, s54, 0x20000
	s_addc_u32 s55, s55, 0
	v_mul_f32_e32 v140, v45, v45
	v_mul_f32_e32 v141, v47, v47
	v_fmac_f32_e32 v140, v44, v44
	v_fmac_f32_e32 v141, v46, v46
	v_add_f32_e32 v142, v140, v141
	v_mul_f32_e32 v140, v41, v41
	v_mul_f32_e32 v141, v43, v43
	v_fmac_f32_e32 v140, v40, v40
	v_fmac_f32_e32 v141, v42, v42
	v_add_f32_e32 v140, v140, v141
	v_add_f32_e32 v142, v142, v140
	v_mul_f32_e32 v140, v37, v37
	v_mul_f32_e32 v141, v39, v39
	v_fmac_f32_e32 v140, v36, v36
	v_fmac_f32_e32 v141, v38, v38
	v_add_f32_e32 v140, v140, v141
	v_add_f32_e32 v142, v142, v140
	v_mul_f32_e32 v140, v33, v33
	v_mul_f32_e32 v141, v35, v35
	v_fmac_f32_e32 v140, v32, v32
	v_fmac_f32_e32 v141, v34, v34
	v_add_f32_e32 v140, v140, v141
	v_add_f32_e32 v142, v142, v140
	v_mov_b32_e32 v32, v142
	s_waitcnt vmcnt(16)
	v_pk_add_f32 v[28:29], v[28:29], v[174:175]
	v_pk_add_f32 v[30:31], v[30:31], v[176:177]
	v_pk_add_f32 v[24:25], v[24:25], v[178:179]
	v_pk_add_f32 v[26:27], v[26:27], v[180:181]
	v_pk_add_f32 v[20:21], v[20:21], v[182:183]
	v_pk_add_f32 v[22:23], v[22:23], v[184:185]
	v_pk_add_f32 v[16:17], v[16:17], v[186:187]
	v_pk_add_f32 v[18:19], v[18:19], v[188:189]
	global_store_dwordx4 v222, v[28:31], s[54:55]
	global_store_dwordx4 v222, v[24:27], s[54:55] offset:64
	global_store_dwordx4 v222, v[20:23], s[54:55] offset:512
	global_store_dwordx4 v222, v[16:19], s[54:55] offset:576
	s_add_u32 s54, s54, 0x20000
	s_addc_u32 s55, s55, 0
	v_mul_f32_e32 v140, v29, v29
	v_mul_f32_e32 v141, v31, v31
	v_fmac_f32_e32 v140, v28, v28
	v_fmac_f32_e32 v141, v30, v30
	v_add_f32_e32 v142, v140, v141
	v_mul_f32_e32 v140, v25, v25
	v_mul_f32_e32 v141, v27, v27
	v_fmac_f32_e32 v140, v24, v24
	v_fmac_f32_e32 v141, v26, v26
	v_add_f32_e32 v140, v140, v141
	v_add_f32_e32 v142, v142, v140
	v_mul_f32_e32 v140, v21, v21
	v_mul_f32_e32 v141, v23, v23
	v_fmac_f32_e32 v140, v20, v20
	v_fmac_f32_e32 v141, v22, v22
	v_add_f32_e32 v140, v140, v141
	v_add_f32_e32 v142, v142, v140
	v_mul_f32_e32 v140, v17, v17
	v_mul_f32_e32 v141, v19, v19
	v_fmac_f32_e32 v140, v16, v16
	v_fmac_f32_e32 v141, v18, v18
	v_add_f32_e32 v140, v140, v141
	v_add_f32_e32 v142, v142, v140
	v_mov_b32_e32 v16, v142
	s_waitcnt vmcnt(12)
	v_pk_add_f32 v[12:13], v[12:13], v[190:191]
	v_pk_add_f32 v[14:15], v[14:15], v[192:193]
	v_pk_add_f32 v[8:9], v[8:9], v[194:195]
	v_pk_add_f32 v[10:11], v[10:11], v[196:197]
	v_pk_add_f32 v[4:5], v[4:5], v[198:199]
	v_pk_add_f32 v[6:7], v[6:7], v[200:201]
	v_pk_add_f32 v[0:1], v[0:1], v[202:203]
	v_pk_add_f32 v[2:3], v[2:3], v[204:205]
	global_store_dwordx4 v222, v[12:15], s[54:55]
	global_store_dwordx4 v222, v[8:11], s[54:55] offset:64
	global_store_dwordx4 v222, v[4:7], s[54:55] offset:512
	global_store_dwordx4 v222, v[0:3], s[54:55] offset:576
	v_mul_f32_e32 v140, v13, v13
	v_mul_f32_e32 v141, v15, v15
	v_fmac_f32_e32 v140, v12, v12
	v_fmac_f32_e32 v141, v14, v14
	v_add_f32_e32 v142, v140, v141
	v_mul_f32_e32 v140, v9, v9
	v_mul_f32_e32 v141, v11, v11
	v_fmac_f32_e32 v140, v8, v8
	v_fmac_f32_e32 v141, v10, v10
	v_add_f32_e32 v140, v140, v141
	v_add_f32_e32 v142, v142, v140
	v_mul_f32_e32 v140, v5, v5
	v_mul_f32_e32 v141, v7, v7
	v_fmac_f32_e32 v140, v4, v4
	v_fmac_f32_e32 v141, v6, v6
	v_add_f32_e32 v140, v140, v141
	v_add_f32_e32 v142, v142, v140
	v_mul_f32_e32 v140, v1, v1
	v_mul_f32_e32 v141, v3, v3
	v_fmac_f32_e32 v140, v0, v0
	v_fmac_f32_e32 v141, v2, v2
	v_add_f32_e32 v140, v140, v141
	v_add_f32_e32 v142, v142, v140
	v_mov_b32_e32 v0, v142
	ds_bpermute_b32 v113, v151, v112
	ds_bpermute_b32 v97, v151, v96
	ds_bpermute_b32 v81, v151, v80
	ds_bpermute_b32 v65, v151, v64
	ds_bpermute_b32 v49, v151, v48
	ds_bpermute_b32 v33, v151, v32
	ds_bpermute_b32 v17, v151, v16
	ds_bpermute_b32 v1, v151, v0
	s_waitcnt lgkmcnt(0)
	v_add_f32_e32 v112, v112, v113
	v_add_f32_e32 v96, v96, v97
	v_add_f32_e32 v80, v80, v81
	v_add_f32_e32 v64, v64, v65
	v_add_f32_e32 v48, v48, v49
	v_add_f32_e32 v32, v32, v33
	v_add_f32_e32 v16, v16, v17
	v_add_f32_e32 v0, v0, v1
	ds_bpermute_b32 v113, v152, v112
	ds_bpermute_b32 v97, v152, v96
	ds_bpermute_b32 v81, v152, v80
	ds_bpermute_b32 v65, v152, v64
	ds_bpermute_b32 v49, v152, v48
	ds_bpermute_b32 v33, v152, v32
	ds_bpermute_b32 v17, v152, v16
	ds_bpermute_b32 v1, v152, v0
	s_waitcnt lgkmcnt(0)
	v_add_f32_e32 v112, v112, v113
	v_add_f32_e32 v96, v96, v97
	v_add_f32_e32 v80, v80, v81
	v_add_f32_e32 v64, v64, v65
	v_add_f32_e32 v48, v48, v49
	v_add_f32_e32 v32, v32, v33
	v_add_f32_e32 v16, v16, v17
	v_add_f32_e32 v0, v0, v1
	s_and_saveexec_b64 s[22:23], s[0:1]
	global_atomic_add_f32 v153, v112, s[58:59]
	global_atomic_add_f32 v153, v96, s[58:59] offset:64
	global_atomic_add_f32 v153, v80, s[58:59] offset:128
	global_atomic_add_f32 v153, v64, s[58:59] offset:192
	global_atomic_add_f32 v153, v48, s[58:59] offset:512
	global_atomic_add_f32 v153, v32, s[58:59] offset:576
	global_atomic_add_f32 v153, v16, s[58:59] offset:640
	global_atomic_add_f32 v153, v0, s[58:59] offset:704
	s_or_b64 exec, exec, s[22:23]
	s_andn2_b64 vcc, exec, s[4:5]
	s_mov_b64 s[4:5], -1
	s_cbranch_vccnz .LBB0_893
	s_andn2_b64 vcc, exec, s[8:9]
	s_cbranch_vccnz .LBB0_892
	s_barrier
	s_branch .LBB0_892
